# X10: X5 + hand-written final-norm loop (all 16 tile pieces + row stats + weights requested up front, one memory round trip per tile)
# speedup vs baseline: 1.0014x; 1.0009x over previous
; __device__ __forceinline__ float lo_dec(unsigned hb, unsigned byte) { return ((float)byte - 128.0f) * lo_scale(hb); }
; __device__ __forceinline__ size_t lo_addr(int pm, int pn, int am, int wave, int lane) { return ((((size_t)(pm * 8 + pn) * 8 + am) * 8 + wave) * 64 + lane) * 16; }
; __device__ __forceinline__ void ph_final(float* out, const bf16* xh, const unsigned char* xl, const rs_t* rowss, const float* w, int vcu, int G, int tid) {
;     const int lane = tid & 63, wave = tid >> 6, wr = wave >> 2, wc = wave & 3, fr = lane & 15, fq = lane >> 4;
;     for (int t = vcu; t < (M / 256) * (DM / 256); t += G) { const int pm = t >> 3, pn = t & 7;
; #pragma unroll
;         for (int am = 0; am < 8; ++am) { const int row = pm * 256 + (am >> 2) * 128 + wr * 64 + (am & 3) * 16 + fr; const float r = 1.0f / sqrtf((float)rowss[row] * (RS_INV / DM) + NORM_EPS);
;             v4u lw = {0x80808080u, 0x80808080u, 0x80808080u, 0x80808080u}; if (MK_LO) lw = *(const v4u*)(xl + pg8::lo_addr(pm, pn, am, wave, lane));
; #pragma unroll
;             for (int bj = 0; bj < 2; ++bj) { const int col = pn * 256 + bj * 128 + wc * 32 + 8 * fq; const size_t o2 = (size_t)row * DM + col; const v4u h = *(const v4u*)(xh + o2);
;                 const f32x4 w0 = *(const f32x4*)(w + col), w1 = *(const f32x4*)(w + col + 4); const unsigned l0 = lw[2 * bj], l1 = lw[2 * bj + 1];
;                 f32x4 v0 = {bflo(h.x) + pg8::lo_dec(h.x & 0xffffu, l0 & 0xffu), bfhi(h.x) + pg8::lo_dec(h.x >> 16, (l0 >> 8) & 0xffu), bflo(h.y) + pg8::lo_dec(h.y & 0xffffu, (l0 >> 16) & 0xffu), bfhi(h.y) + pg8::lo_dec(h.y >> 16, l0 >> 24)};
;                 f32x4 v1 = {bflo(h.z) + pg8::lo_dec(h.z & 0xffffu, l1 & 0xffu), bfhi(h.z) + pg8::lo_dec(h.z >> 16, (l1 >> 8) & 0xffu), bflo(h.w) + pg8::lo_dec(h.w & 0xffffu, (l1 >> 16) & 0xffu), bfhi(h.w) + pg8::lo_dec(h.w >> 16, l1 >> 24)};
;                 *(f32x4*)(out + o2) = v0 * r * w0; *(f32x4*)(out + o2 + 4) = v1 * r * w1; } } }
.LBB0_1812:
	s_and_b32 s0, s6, 0xffffff00
	s_and_b32 s1, s9, 0x700
	v_or_b32_e32 v0, s0, v62
	v_or_b32_e32 v1, s1, v63
	v_lshlrev_b32_e32 v2, 2, v0
	v_lshl_add_u32 v3, v0, 11, v1
	v_lshlrev_b32_e32 v8, 1, v3
	global_load_dword v16, v2, s[4:5] offset:0
	global_load_dword v17, v2, s[4:5] offset:64
	global_load_dword v18, v2, s[4:5] offset:128
	global_load_dword v19, v2, s[4:5] offset:192
	global_load_dword v20, v2, s[4:5] offset:512
	global_load_dword v21, v2, s[4:5] offset:576
	global_load_dword v22, v2, s[4:5] offset:640
	global_load_dword v23, v2, s[4:5] offset:704
	v_add_u32_e32 v9, 0x10000, v8
	v_add_u32_e32 v10, 0x20000, v8
	v_add_u32_e32 v11, 0x30000, v8
	v_add_u32_e32 v12, 0x80000, v8
	v_add_u32_e32 v13, 0x90000, v8
	v_add_u32_e32 v14, 0xa0000, v8
	v_add_u32_e32 v15, 0xb0000, v8
	v_lshlrev_b32_e32 v40, 2, v1
	global_load_dwordx4 v[24:27], v40, s[14:15]
	global_load_dwordx4 v[28:31], v40, s[14:15] offset:16
	global_load_dwordx4 v[32:35], v40, s[14:15] offset:512
	global_load_dwordx4 v[36:39], v40, s[14:15] offset:528
	global_load_dwordx4 v[100:103], v8, s[2:3]
	global_load_dwordx4 v[104:107], v8, s[2:3] offset:256
	global_load_dwordx4 v[108:111], v9, s[2:3]
	global_load_dwordx4 v[112:115], v9, s[2:3] offset:256
	global_load_dwordx4 v[116:119], v10, s[2:3]
	global_load_dwordx4 v[120:123], v10, s[2:3] offset:256
	global_load_dwordx4 v[124:127], v11, s[2:3]
	global_load_dwordx4 v[128:131], v11, s[2:3] offset:256
	global_load_dwordx4 v[132:135], v12, s[2:3]
	global_load_dwordx4 v[136:139], v12, s[2:3] offset:256
	global_load_dwordx4 v[140:143], v13, s[2:3]
	global_load_dwordx4 v[144:147], v13, s[2:3] offset:256
	global_load_dwordx4 v[148:151], v14, s[2:3]
	global_load_dwordx4 v[152:155], v14, s[2:3] offset:256
	global_load_dwordx4 v[156:159], v15, s[2:3]
	global_load_dwordx4 v[160:163], v15, s[2:3] offset:256
	s_add_i32 s10, s10, s62
	s_add_i32 s9, s9, s11
	s_add_i32 s6, s6, s7
	s_waitcnt vmcnt(20)
	v_cvt_f32_u32_e32 v16, v16
	v_fmamk_f32 v16, v16, 0x35000000, v64
	v_cmp_gt_f32_e32 vcc, s8, v16
	v_mul_f32_e32 v42, 0x4f800000, v16
	s_nop 0
	v_cndmask_b32_e32 v16, v16, v42, vcc
	v_sqrt_f32_e32 v42, v16
	s_nop 0
	v_add_u32_e32 v43, -1, v42
	v_add_u32_e32 v44, 1, v42
	v_fma_f32 v45, -v43, v42, v16
	v_fma_f32 v46, -v44, v42, v16
	v_cmp_ge_f32_e64 s[0:1], 0, v45
	s_nop 1
	v_cndmask_b32_e64 v42, v42, v43, s[0:1]
	v_cmp_lt_f32_e64 s[0:1], 0, v46
	s_nop 1
	v_cndmask_b32_e64 v42, v42, v44, s[0:1]
	v_mul_f32_e32 v43, 0x37800000, v42
	s_nop 0
	v_cndmask_b32_e32 v42, v42, v43, vcc
	v_cmp_class_f32_e32 vcc, v16, v65
	s_nop 1
	v_cndmask_b32_e32 v16, v42, v16, vcc
	v_div_scale_f32 v42, s[0:1], v16, v16, 1.0
	v_rcp_f32_e32 v44, v42
	v_div_scale_f32 v43, vcc, 1.0, v16, 1.0
	v_fma_f32 v45, -v42, v44, 1.0
	v_fmac_f32_e32 v44, v45, v44
	v_mul_f32_e32 v45, v43, v44
	v_fma_f32 v46, -v42, v45, v43
	v_fmac_f32_e32 v45, v46, v44
	v_fma_f32 v42, -v42, v45, v43
	v_div_fmas_f32 v42, v42, v44, v45
	v_div_fixup_f32 v16, v42, v16, 1.0
	v_cvt_f32_u32_e32 v17, v17
	v_fmamk_f32 v17, v17, 0x35000000, v64
	v_cmp_gt_f32_e32 vcc, s8, v17
	v_mul_f32_e32 v42, 0x4f800000, v17
	s_nop 0
	v_cndmask_b32_e32 v17, v17, v42, vcc
	v_sqrt_f32_e32 v42, v17
	s_nop 0
	v_add_u32_e32 v43, -1, v42
	v_add_u32_e32 v44, 1, v42
	v_fma_f32 v45, -v43, v42, v17
	v_fma_f32 v46, -v44, v42, v17
	v_cmp_ge_f32_e64 s[0:1], 0, v45
	s_nop 1
	v_cndmask_b32_e64 v42, v42, v43, s[0:1]
	v_cmp_lt_f32_e64 s[0:1], 0, v46
	s_nop 1
	v_cndmask_b32_e64 v42, v42, v44, s[0:1]
	v_mul_f32_e32 v43, 0x37800000, v42
	s_nop 0
	v_cndmask_b32_e32 v42, v42, v43, vcc
	v_cmp_class_f32_e32 vcc, v17, v65
	s_nop 1
	v_cndmask_b32_e32 v17, v42, v17, vcc
	v_div_scale_f32 v42, s[0:1], v17, v17, 1.0
	v_rcp_f32_e32 v44, v42
	v_div_scale_f32 v43, vcc, 1.0, v17, 1.0
	v_fma_f32 v45, -v42, v44, 1.0
	v_fmac_f32_e32 v44, v45, v44
	v_mul_f32_e32 v45, v43, v44
	v_fma_f32 v46, -v42, v45, v43
	v_fmac_f32_e32 v45, v46, v44
	v_fma_f32 v42, -v42, v45, v43
	v_div_fmas_f32 v42, v42, v44, v45
	v_div_fixup_f32 v17, v42, v17, 1.0
	v_cvt_f32_u32_e32 v18, v18
	v_fmamk_f32 v18, v18, 0x35000000, v64
	v_cmp_gt_f32_e32 vcc, s8, v18
	v_mul_f32_e32 v42, 0x4f800000, v18
	s_nop 0
	v_cndmask_b32_e32 v18, v18, v42, vcc
	v_sqrt_f32_e32 v42, v18
	s_nop 0
	v_add_u32_e32 v43, -1, v42
	v_add_u32_e32 v44, 1, v42
	v_fma_f32 v45, -v43, v42, v18
	v_fma_f32 v46, -v44, v42, v18
	v_cmp_ge_f32_e64 s[0:1], 0, v45
	s_nop 1
	v_cndmask_b32_e64 v42, v42, v43, s[0:1]
	v_cmp_lt_f32_e64 s[0:1], 0, v46
	s_nop 1
	v_cndmask_b32_e64 v42, v42, v44, s[0:1]
	v_mul_f32_e32 v43, 0x37800000, v42
	s_nop 0
	v_cndmask_b32_e32 v42, v42, v43, vcc
	v_cmp_class_f32_e32 vcc, v18, v65
	s_nop 1
	v_cndmask_b32_e32 v18, v42, v18, vcc
	v_div_scale_f32 v42, s[0:1], v18, v18, 1.0
	v_rcp_f32_e32 v44, v42
	v_div_scale_f32 v43, vcc, 1.0, v18, 1.0
	v_fma_f32 v45, -v42, v44, 1.0
	v_fmac_f32_e32 v44, v45, v44
	v_mul_f32_e32 v45, v43, v44
	v_fma_f32 v46, -v42, v45, v43
	v_fmac_f32_e32 v45, v46, v44
	v_fma_f32 v42, -v42, v45, v43
	v_div_fmas_f32 v42, v42, v44, v45
	v_div_fixup_f32 v18, v42, v18, 1.0
	v_cvt_f32_u32_e32 v19, v19
	v_fmamk_f32 v19, v19, 0x35000000, v64
	v_cmp_gt_f32_e32 vcc, s8, v19
	v_mul_f32_e32 v42, 0x4f800000, v19
	s_nop 0
	v_cndmask_b32_e32 v19, v19, v42, vcc
	v_sqrt_f32_e32 v42, v19
	s_nop 0
	v_add_u32_e32 v43, -1, v42
	v_add_u32_e32 v44, 1, v42
	v_fma_f32 v45, -v43, v42, v19
	v_fma_f32 v46, -v44, v42, v19
	v_cmp_ge_f32_e64 s[0:1], 0, v45
	s_nop 1
	v_cndmask_b32_e64 v42, v42, v43, s[0:1]
	v_cmp_lt_f32_e64 s[0:1], 0, v46
	s_nop 1
	v_cndmask_b32_e64 v42, v42, v44, s[0:1]
	v_mul_f32_e32 v43, 0x37800000, v42
	s_nop 0
	v_cndmask_b32_e32 v42, v42, v43, vcc
	v_cmp_class_f32_e32 vcc, v19, v65
	s_nop 1
; __device__ __forceinline__ float lo_dec(unsigned hb, unsigned byte) { return ((float)byte - 128.0f) * lo_scale(hb); }
; __device__ __forceinline__ size_t lo_addr(int pm, int pn, int am, int wave, int lane) { return ((((size_t)(pm * 8 + pn) * 8 + am) * 8 + wave) * 64 + lane) * 16; }
; __device__ __forceinline__ void ph_final(float* out, const bf16* xh, const unsigned char* xl, const rs_t* rowss, const float* w, int vcu, int G, int tid) {
;     ...
;         for (int am = 0; am < 8; ++am) { const int row = pm * 256 + (am >> 2) * 128 + wr * 64 + (am & 3) * 16 + fr; const float r = 1.0f / sqrtf((float)rowss[row] * (RS_INV / DM) + NORM_EPS);
;             v4u lw = {0x80808080u, 0x80808080u, 0x80808080u, 0x80808080u}; if (MK_LO) lw = *(const v4u*)(xl + pg8::lo_addr(pm, pn, am, wave, lane));
; #pragma unroll
;             for (int bj = 0; bj < 2; ++bj) { const int col = pn * 256 + bj * 128 + wc * 32 + 8 * fq; const size_t o2 = (size_t)row * DM + col; const v4u h = *(const v4u*)(xh + o2);
;                 const f32x4 w0 = *(const f32x4*)(w + col), w1 = *(const f32x4*)(w + col + 4); const unsigned l0 = lw[2 * bj], l1 = lw[2 * bj + 1];
;                 f32x4 v0 = {bflo(h.x) + pg8::lo_dec(h.x & 0xffffu, l0 & 0xffu), bfhi(h.x) + pg8::lo_dec(h.x >> 16, (l0 >> 8) & 0xffu), bflo(h.y) + pg8::lo_dec(h.y & 0xffffu, (l0 >> 16) & 0xffu), bfhi(h.y) + pg8::lo_dec(h.y >> 16, l0 >> 24)};
;                 f32x4 v1 = {bflo(h.z) + pg8::lo_dec(h.z & 0xffffu, l1 & 0xffu), bfhi(h.z) + pg8::lo_dec(h.z >> 16, (l1 >> 8) & 0xffu), bflo(h.w) + pg8::lo_dec(h.w & 0xffffu, (l1 >> 16) & 0xffu), bfhi(h.w) + pg8::lo_dec(h.w >> 16, l1 >> 24)};
;                 *(f32x4*)(out + o2) = v0 * r * w0; *(f32x4*)(out + o2 + 4) = v1 * r * w1; } } }
	v_cndmask_b32_e32 v19, v42, v19, vcc
	v_div_scale_f32 v42, s[0:1], v19, v19, 1.0
	v_rcp_f32_e32 v44, v42
	v_div_scale_f32 v43, vcc, 1.0, v19, 1.0
	v_fma_f32 v45, -v42, v44, 1.0
	v_fmac_f32_e32 v44, v45, v44
	v_mul_f32_e32 v45, v43, v44
	v_fma_f32 v46, -v42, v45, v43
	v_fmac_f32_e32 v45, v46, v44
	v_fma_f32 v42, -v42, v45, v43
	v_div_fmas_f32 v42, v42, v44, v45
	v_div_fixup_f32 v19, v42, v19, 1.0
	v_cvt_f32_u32_e32 v20, v20
	v_fmamk_f32 v20, v20, 0x35000000, v64
	v_cmp_gt_f32_e32 vcc, s8, v20
	v_mul_f32_e32 v42, 0x4f800000, v20
	s_nop 0
	v_cndmask_b32_e32 v20, v20, v42, vcc
	v_sqrt_f32_e32 v42, v20
	s_nop 0
	v_add_u32_e32 v43, -1, v42
	v_add_u32_e32 v44, 1, v42
	v_fma_f32 v45, -v43, v42, v20
	v_fma_f32 v46, -v44, v42, v20
	v_cmp_ge_f32_e64 s[0:1], 0, v45
	s_nop 1
	v_cndmask_b32_e64 v42, v42, v43, s[0:1]
	v_cmp_lt_f32_e64 s[0:1], 0, v46
	s_nop 1
	v_cndmask_b32_e64 v42, v42, v44, s[0:1]
	v_mul_f32_e32 v43, 0x37800000, v42
	s_nop 0
	v_cndmask_b32_e32 v42, v42, v43, vcc
	v_cmp_class_f32_e32 vcc, v20, v65
	s_nop 1
	v_cndmask_b32_e32 v20, v42, v20, vcc
	v_div_scale_f32 v42, s[0:1], v20, v20, 1.0
	v_rcp_f32_e32 v44, v42
	v_div_scale_f32 v43, vcc, 1.0, v20, 1.0
	v_fma_f32 v45, -v42, v44, 1.0
	v_fmac_f32_e32 v44, v45, v44
	v_mul_f32_e32 v45, v43, v44
	v_fma_f32 v46, -v42, v45, v43
	v_fmac_f32_e32 v45, v46, v44
	v_fma_f32 v42, -v42, v45, v43
	v_div_fmas_f32 v42, v42, v44, v45
	v_div_fixup_f32 v20, v42, v20, 1.0
	v_cvt_f32_u32_e32 v21, v21
	v_fmamk_f32 v21, v21, 0x35000000, v64
	v_cmp_gt_f32_e32 vcc, s8, v21
	v_mul_f32_e32 v42, 0x4f800000, v21
	s_nop 0
	v_cndmask_b32_e32 v21, v21, v42, vcc
	v_sqrt_f32_e32 v42, v21
	s_nop 0
	v_add_u32_e32 v43, -1, v42
	v_add_u32_e32 v44, 1, v42
	v_fma_f32 v45, -v43, v42, v21
	v_fma_f32 v46, -v44, v42, v21
	v_cmp_ge_f32_e64 s[0:1], 0, v45
	s_nop 1
	v_cndmask_b32_e64 v42, v42, v43, s[0:1]
	v_cmp_lt_f32_e64 s[0:1], 0, v46
	s_nop 1
	v_cndmask_b32_e64 v42, v42, v44, s[0:1]
	v_mul_f32_e32 v43, 0x37800000, v42
	s_nop 0
	v_cndmask_b32_e32 v42, v42, v43, vcc
	v_cmp_class_f32_e32 vcc, v21, v65
	s_nop 1
	v_cndmask_b32_e32 v21, v42, v21, vcc
	v_div_scale_f32 v42, s[0:1], v21, v21, 1.0
	v_rcp_f32_e32 v44, v42
	v_div_scale_f32 v43, vcc, 1.0, v21, 1.0
	v_fma_f32 v45, -v42, v44, 1.0
	v_fmac_f32_e32 v44, v45, v44
	v_mul_f32_e32 v45, v43, v44
	v_fma_f32 v46, -v42, v45, v43
	v_fmac_f32_e32 v45, v46, v44
	v_fma_f32 v42, -v42, v45, v43
	v_div_fmas_f32 v42, v42, v44, v45
	v_div_fixup_f32 v21, v42, v21, 1.0
	v_cvt_f32_u32_e32 v22, v22
	v_fmamk_f32 v22, v22, 0x35000000, v64
	v_cmp_gt_f32_e32 vcc, s8, v22
	v_mul_f32_e32 v42, 0x4f800000, v22
	s_nop 0
	v_cndmask_b32_e32 v22, v22, v42, vcc
	v_sqrt_f32_e32 v42, v22
	s_nop 0
	v_add_u32_e32 v43, -1, v42
	v_add_u32_e32 v44, 1, v42
	v_fma_f32 v45, -v43, v42, v22
	v_fma_f32 v46, -v44, v42, v22
	v_cmp_ge_f32_e64 s[0:1], 0, v45
	s_nop 1
	v_cndmask_b32_e64 v42, v42, v43, s[0:1]
	v_cmp_lt_f32_e64 s[0:1], 0, v46
	s_nop 1
	v_cndmask_b32_e64 v42, v42, v44, s[0:1]
	v_mul_f32_e32 v43, 0x37800000, v42
	s_nop 0
	v_cndmask_b32_e32 v42, v42, v43, vcc
	v_cmp_class_f32_e32 vcc, v22, v65
	s_nop 1
	v_cndmask_b32_e32 v22, v42, v22, vcc
	v_div_scale_f32 v42, s[0:1], v22, v22, 1.0
	v_rcp_f32_e32 v44, v42
	v_div_scale_f32 v43, vcc, 1.0, v22, 1.0
	v_fma_f32 v45, -v42, v44, 1.0
	v_fmac_f32_e32 v44, v45, v44
	v_mul_f32_e32 v45, v43, v44
	v_fma_f32 v46, -v42, v45, v43
	v_fmac_f32_e32 v45, v46, v44
	v_fma_f32 v42, -v42, v45, v43
	v_div_fmas_f32 v42, v42, v44, v45
	v_div_fixup_f32 v22, v42, v22, 1.0
	v_cvt_f32_u32_e32 v23, v23
	v_fmamk_f32 v23, v23, 0x35000000, v64
	v_cmp_gt_f32_e32 vcc, s8, v23
	v_mul_f32_e32 v42, 0x4f800000, v23
	s_nop 0
	v_cndmask_b32_e32 v23, v23, v42, vcc
	v_sqrt_f32_e32 v42, v23
	s_nop 0
	v_add_u32_e32 v43, -1, v42
	v_add_u32_e32 v44, 1, v42
	v_fma_f32 v45, -v43, v42, v23
	v_fma_f32 v46, -v44, v42, v23
	v_cmp_ge_f32_e64 s[0:1], 0, v45
	s_nop 1
	v_cndmask_b32_e64 v42, v42, v43, s[0:1]
	v_cmp_lt_f32_e64 s[0:1], 0, v46
	s_nop 1
	v_cndmask_b32_e64 v42, v42, v44, s[0:1]
	v_mul_f32_e32 v43, 0x37800000, v42
	s_nop 0
	v_cndmask_b32_e32 v42, v42, v43, vcc
	v_cmp_class_f32_e32 vcc, v23, v65
	s_nop 1
	v_cndmask_b32_e32 v23, v42, v23, vcc
	v_div_scale_f32 v42, s[0:1], v23, v23, 1.0
	v_rcp_f32_e32 v44, v42
	v_div_scale_f32 v43, vcc, 1.0, v23, 1.0
	v_fma_f32 v45, -v42, v44, 1.0
	v_fmac_f32_e32 v44, v45, v44
	v_mul_f32_e32 v45, v43, v44
	v_fma_f32 v46, -v42, v45, v43
	v_fmac_f32_e32 v45, v46, v44
	v_fma_f32 v42, -v42, v45, v43
	v_div_fmas_f32 v42, v42, v44, v45
	v_div_fixup_f32 v23, v42, v23, 1.0
	s_cmpk_lt_i32 s10, 0x400
	v_lshlrev_b32_e32 v56, 1, v8
	v_mov_b32_e32 v58, v16
	s_waitcnt vmcnt(15)
	v_lshlrev_b32_e32 v48, 16, v100
	v_and_b32_e32 v49, 0xffff0000, v100
	v_lshlrev_b32_e32 v50, 16, v101
	v_and_b32_e32 v51, 0xffff0000, v101
	v_lshlrev_b32_e32 v52, 16, v102
	v_and_b32_e32 v53, 0xffff0000, v102
	v_lshlrev_b32_e32 v54, 16, v103
	v_and_b32_e32 v55, 0xffff0000, v103
	v_pk_mul_f32 v[48:49], v[58:59], v[48:49] op_sel_hi:[0,1]
	v_pk_mul_f32 v[50:51], v[58:59], v[50:51] op_sel_hi:[0,1]
	v_pk_mul_f32 v[52:53], v[58:59], v[52:53] op_sel_hi:[0,1]
	v_pk_mul_f32 v[54:55], v[58:59], v[54:55] op_sel_hi:[0,1]
	v_pk_mul_f32 v[48:49], v[24:25], v[48:49]
	v_pk_mul_f32 v[50:51], v[26:27], v[50:51]
	v_pk_mul_f32 v[52:53], v[28:29], v[52:53]
	v_pk_mul_f32 v[54:55], v[30:31], v[54:55]
	global_store_dwordx4 v56, v[48:51], s[16:17]
	global_store_dwordx4 v56, v[52:55], s[16:17] offset:16
	s_nop 1
	s_waitcnt vmcnt(16)
; __device__ __forceinline__ float lo_dec(unsigned hb, unsigned byte) { return ((float)byte - 128.0f) * lo_scale(hb); }
; __device__ __forceinline__ void ph_final(float* out, const bf16* xh, const unsigned char* xl, const rs_t* rowss, const float* w, int vcu, int G, int tid) {
;     ...
;             for (int bj = 0; bj < 2; ++bj) { const int col = pn * 256 + bj * 128 + wc * 32 + 8 * fq; const size_t o2 = (size_t)row * DM + col; const v4u h = *(const v4u*)(xh + o2);
;                 const f32x4 w0 = *(const f32x4*)(w + col), w1 = *(const f32x4*)(w + col + 4); const unsigned l0 = lw[2 * bj], l1 = lw[2 * bj + 1];
;                 f32x4 v0 = {bflo(h.x) + pg8::lo_dec(h.x & 0xffffu, l0 & 0xffu), bfhi(h.x) + pg8::lo_dec(h.x >> 16, (l0 >> 8) & 0xffu), bflo(h.y) + pg8::lo_dec(h.y & 0xffffu, (l0 >> 16) & 0xffu), bfhi(h.y) + pg8::lo_dec(h.y >> 16, l0 >> 24)};
;                 f32x4 v1 = {bflo(h.z) + pg8::lo_dec(h.z & 0xffffu, l1 & 0xffu), bfhi(h.z) + pg8::lo_dec(h.z >> 16, (l1 >> 8) & 0xffu), bflo(h.w) + pg8::lo_dec(h.w & 0xffffu, (l1 >> 16) & 0xffu), bfhi(h.w) + pg8::lo_dec(h.w >> 16, l1 >> 24)};
;                 *(f32x4*)(out + o2) = v0 * r * w0; *(f32x4*)(out + o2 + 4) = v1 * r * w1; } } }
	v_lshlrev_b32_e32 v48, 16, v104
	v_and_b32_e32 v49, 0xffff0000, v104
	v_lshlrev_b32_e32 v50, 16, v105
	v_and_b32_e32 v51, 0xffff0000, v105
	v_lshlrev_b32_e32 v52, 16, v106
	v_and_b32_e32 v53, 0xffff0000, v106
	v_lshlrev_b32_e32 v54, 16, v107
	v_and_b32_e32 v55, 0xffff0000, v107
	v_pk_mul_f32 v[48:49], v[58:59], v[48:49] op_sel_hi:[0,1]
	v_pk_mul_f32 v[50:51], v[58:59], v[50:51] op_sel_hi:[0,1]
	v_pk_mul_f32 v[52:53], v[58:59], v[52:53] op_sel_hi:[0,1]
	v_pk_mul_f32 v[54:55], v[58:59], v[54:55] op_sel_hi:[0,1]
	v_pk_mul_f32 v[48:49], v[32:33], v[48:49]
	v_pk_mul_f32 v[50:51], v[34:35], v[50:51]
	v_pk_mul_f32 v[52:53], v[36:37], v[52:53]
	v_pk_mul_f32 v[54:55], v[38:39], v[54:55]
	global_store_dwordx4 v56, v[48:51], s[16:17] offset:512
	global_store_dwordx4 v56, v[52:55], s[16:17] offset:528
	s_nop 1
	v_lshlrev_b32_e32 v56, 1, v9
	v_mov_b32_e32 v58, v17
	s_waitcnt vmcnt(17)
	v_lshlrev_b32_e32 v48, 16, v108
	v_and_b32_e32 v49, 0xffff0000, v108
	v_lshlrev_b32_e32 v50, 16, v109
	v_and_b32_e32 v51, 0xffff0000, v109
	v_lshlrev_b32_e32 v52, 16, v110
	v_and_b32_e32 v53, 0xffff0000, v110
	v_lshlrev_b32_e32 v54, 16, v111
	v_and_b32_e32 v55, 0xffff0000, v111
	v_pk_mul_f32 v[48:49], v[58:59], v[48:49] op_sel_hi:[0,1]
	v_pk_mul_f32 v[50:51], v[58:59], v[50:51] op_sel_hi:[0,1]
	v_pk_mul_f32 v[52:53], v[58:59], v[52:53] op_sel_hi:[0,1]
	v_pk_mul_f32 v[54:55], v[58:59], v[54:55] op_sel_hi:[0,1]
	v_pk_mul_f32 v[48:49], v[24:25], v[48:49]
	v_pk_mul_f32 v[50:51], v[26:27], v[50:51]
	v_pk_mul_f32 v[52:53], v[28:29], v[52:53]
	v_pk_mul_f32 v[54:55], v[30:31], v[54:55]
	global_store_dwordx4 v56, v[48:51], s[16:17]
	global_store_dwordx4 v56, v[52:55], s[16:17] offset:16
	s_nop 1
	s_waitcnt vmcnt(18)
	v_lshlrev_b32_e32 v48, 16, v112
	v_and_b32_e32 v49, 0xffff0000, v112
	v_lshlrev_b32_e32 v50, 16, v113
	v_and_b32_e32 v51, 0xffff0000, v113
	v_lshlrev_b32_e32 v52, 16, v114
	v_and_b32_e32 v53, 0xffff0000, v114
	v_lshlrev_b32_e32 v54, 16, v115
	v_and_b32_e32 v55, 0xffff0000, v115
	v_pk_mul_f32 v[48:49], v[58:59], v[48:49] op_sel_hi:[0,1]
	v_pk_mul_f32 v[50:51], v[58:59], v[50:51] op_sel_hi:[0,1]
	v_pk_mul_f32 v[52:53], v[58:59], v[52:53] op_sel_hi:[0,1]
	v_pk_mul_f32 v[54:55], v[58:59], v[54:55] op_sel_hi:[0,1]
	v_pk_mul_f32 v[48:49], v[32:33], v[48:49]
	v_pk_mul_f32 v[50:51], v[34:35], v[50:51]
	v_pk_mul_f32 v[52:53], v[36:37], v[52:53]
	v_pk_mul_f32 v[54:55], v[38:39], v[54:55]
	global_store_dwordx4 v56, v[48:51], s[16:17] offset:512
	global_store_dwordx4 v56, v[52:55], s[16:17] offset:528
	s_nop 1
	v_lshlrev_b32_e32 v56, 1, v10
	v_mov_b32_e32 v58, v18
	s_waitcnt vmcnt(19)
	v_lshlrev_b32_e32 v48, 16, v116
	v_and_b32_e32 v49, 0xffff0000, v116
	v_lshlrev_b32_e32 v50, 16, v117
	v_and_b32_e32 v51, 0xffff0000, v117
	v_lshlrev_b32_e32 v52, 16, v118
	v_and_b32_e32 v53, 0xffff0000, v118
	v_lshlrev_b32_e32 v54, 16, v119
	v_and_b32_e32 v55, 0xffff0000, v119
	v_pk_mul_f32 v[48:49], v[58:59], v[48:49] op_sel_hi:[0,1]
	v_pk_mul_f32 v[50:51], v[58:59], v[50:51] op_sel_hi:[0,1]
	v_pk_mul_f32 v[52:53], v[58:59], v[52:53] op_sel_hi:[0,1]
	v_pk_mul_f32 v[54:55], v[58:59], v[54:55] op_sel_hi:[0,1]
	v_pk_mul_f32 v[48:49], v[24:25], v[48:49]
	v_pk_mul_f32 v[50:51], v[26:27], v[50:51]
	v_pk_mul_f32 v[52:53], v[28:29], v[52:53]
	v_pk_mul_f32 v[54:55], v[30:31], v[54:55]
	global_store_dwordx4 v56, v[48:51], s[16:17]
	global_store_dwordx4 v56, v[52:55], s[16:17] offset:16
	s_nop 1
	s_waitcnt vmcnt(20)
	v_lshlrev_b32_e32 v48, 16, v120
	v_and_b32_e32 v49, 0xffff0000, v120
	v_lshlrev_b32_e32 v50, 16, v121
	v_and_b32_e32 v51, 0xffff0000, v121
	v_lshlrev_b32_e32 v52, 16, v122
	v_and_b32_e32 v53, 0xffff0000, v122
	v_lshlrev_b32_e32 v54, 16, v123
	v_and_b32_e32 v55, 0xffff0000, v123
	v_pk_mul_f32 v[48:49], v[58:59], v[48:49] op_sel_hi:[0,1]
	v_pk_mul_f32 v[50:51], v[58:59], v[50:51] op_sel_hi:[0,1]
	v_pk_mul_f32 v[52:53], v[58:59], v[52:53] op_sel_hi:[0,1]
	v_pk_mul_f32 v[54:55], v[58:59], v[54:55] op_sel_hi:[0,1]
	v_pk_mul_f32 v[48:49], v[32:33], v[48:49]
	v_pk_mul_f32 v[50:51], v[34:35], v[50:51]
	v_pk_mul_f32 v[52:53], v[36:37], v[52:53]
	v_pk_mul_f32 v[54:55], v[38:39], v[54:55]
	global_store_dwordx4 v56, v[48:51], s[16:17] offset:512
	global_store_dwordx4 v56, v[52:55], s[16:17] offset:528
	s_nop 1
	v_lshlrev_b32_e32 v56, 1, v11
	v_mov_b32_e32 v58, v19
	s_waitcnt vmcnt(21)
	v_lshlrev_b32_e32 v48, 16, v124
	v_and_b32_e32 v49, 0xffff0000, v124
	v_lshlrev_b32_e32 v50, 16, v125
	v_and_b32_e32 v51, 0xffff0000, v125
	v_lshlrev_b32_e32 v52, 16, v126
	v_and_b32_e32 v53, 0xffff0000, v126
	v_lshlrev_b32_e32 v54, 16, v127
	v_and_b32_e32 v55, 0xffff0000, v127
	v_pk_mul_f32 v[48:49], v[58:59], v[48:49] op_sel_hi:[0,1]
	v_pk_mul_f32 v[50:51], v[58:59], v[50:51] op_sel_hi:[0,1]
	v_pk_mul_f32 v[52:53], v[58:59], v[52:53] op_sel_hi:[0,1]
	v_pk_mul_f32 v[54:55], v[58:59], v[54:55] op_sel_hi:[0,1]
	v_pk_mul_f32 v[48:49], v[24:25], v[48:49]
	v_pk_mul_f32 v[50:51], v[26:27], v[50:51]
	v_pk_mul_f32 v[52:53], v[28:29], v[52:53]
	v_pk_mul_f32 v[54:55], v[30:31], v[54:55]
	global_store_dwordx4 v56, v[48:51], s[16:17]
	global_store_dwordx4 v56, v[52:55], s[16:17] offset:16
	s_nop 1
	s_waitcnt vmcnt(22)
	v_lshlrev_b32_e32 v48, 16, v128
	v_and_b32_e32 v49, 0xffff0000, v128
	v_lshlrev_b32_e32 v50, 16, v129
	v_and_b32_e32 v51, 0xffff0000, v129
	v_lshlrev_b32_e32 v52, 16, v130
	v_and_b32_e32 v53, 0xffff0000, v130
	v_lshlrev_b32_e32 v54, 16, v131
	v_and_b32_e32 v55, 0xffff0000, v131
	v_pk_mul_f32 v[48:49], v[58:59], v[48:49] op_sel_hi:[0,1]
	v_pk_mul_f32 v[50:51], v[58:59], v[50:51] op_sel_hi:[0,1]
	v_pk_mul_f32 v[52:53], v[58:59], v[52:53] op_sel_hi:[0,1]
	v_pk_mul_f32 v[54:55], v[58:59], v[54:55] op_sel_hi:[0,1]
	v_pk_mul_f32 v[48:49], v[32:33], v[48:49]
	v_pk_mul_f32 v[50:51], v[34:35], v[50:51]
	v_pk_mul_f32 v[52:53], v[36:37], v[52:53]
	v_pk_mul_f32 v[54:55], v[38:39], v[54:55]
	global_store_dwordx4 v56, v[48:51], s[16:17] offset:512
	global_store_dwordx4 v56, v[52:55], s[16:17] offset:528
	s_nop 1
	v_lshlrev_b32_e32 v56, 1, v12
	v_mov_b32_e32 v58, v20
	s_waitcnt vmcnt(23)
; __device__ __forceinline__ float lo_dec(unsigned hb, unsigned byte) { return ((float)byte - 128.0f) * lo_scale(hb); }
; __device__ __forceinline__ void ph_final(float* out, const bf16* xh, const unsigned char* xl, const rs_t* rowss, const float* w, int vcu, int G, int tid) {
;     ...
;             for (int bj = 0; bj < 2; ++bj) { const int col = pn * 256 + bj * 128 + wc * 32 + 8 * fq; const size_t o2 = (size_t)row * DM + col; const v4u h = *(const v4u*)(xh + o2);
;                 const f32x4 w0 = *(const f32x4*)(w + col), w1 = *(const f32x4*)(w + col + 4); const unsigned l0 = lw[2 * bj], l1 = lw[2 * bj + 1];
;                 f32x4 v0 = {bflo(h.x) + pg8::lo_dec(h.x & 0xffffu, l0 & 0xffu), bfhi(h.x) + pg8::lo_dec(h.x >> 16, (l0 >> 8) & 0xffu), bflo(h.y) + pg8::lo_dec(h.y & 0xffffu, (l0 >> 16) & 0xffu), bfhi(h.y) + pg8::lo_dec(h.y >> 16, l0 >> 24)};
;                 f32x4 v1 = {bflo(h.z) + pg8::lo_dec(h.z & 0xffffu, l1 & 0xffu), bfhi(h.z) + pg8::lo_dec(h.z >> 16, (l1 >> 8) & 0xffu), bflo(h.w) + pg8::lo_dec(h.w & 0xffffu, (l1 >> 16) & 0xffu), bfhi(h.w) + pg8::lo_dec(h.w >> 16, l1 >> 24)};
;                 *(f32x4*)(out + o2) = v0 * r * w0; *(f32x4*)(out + o2 + 4) = v1 * r * w1; } } }
	v_lshlrev_b32_e32 v48, 16, v132
	v_and_b32_e32 v49, 0xffff0000, v132
	v_lshlrev_b32_e32 v50, 16, v133
	v_and_b32_e32 v51, 0xffff0000, v133
	v_lshlrev_b32_e32 v52, 16, v134
	v_and_b32_e32 v53, 0xffff0000, v134
	v_lshlrev_b32_e32 v54, 16, v135
	v_and_b32_e32 v55, 0xffff0000, v135
	v_pk_mul_f32 v[48:49], v[58:59], v[48:49] op_sel_hi:[0,1]
	v_pk_mul_f32 v[50:51], v[58:59], v[50:51] op_sel_hi:[0,1]
	v_pk_mul_f32 v[52:53], v[58:59], v[52:53] op_sel_hi:[0,1]
	v_pk_mul_f32 v[54:55], v[58:59], v[54:55] op_sel_hi:[0,1]
	v_pk_mul_f32 v[48:49], v[24:25], v[48:49]
	v_pk_mul_f32 v[50:51], v[26:27], v[50:51]
	v_pk_mul_f32 v[52:53], v[28:29], v[52:53]
	v_pk_mul_f32 v[54:55], v[30:31], v[54:55]
	global_store_dwordx4 v56, v[48:51], s[16:17]
	global_store_dwordx4 v56, v[52:55], s[16:17] offset:16
	s_nop 1
	s_waitcnt vmcnt(24)
	v_lshlrev_b32_e32 v48, 16, v136
	v_and_b32_e32 v49, 0xffff0000, v136
	v_lshlrev_b32_e32 v50, 16, v137
	v_and_b32_e32 v51, 0xffff0000, v137
	v_lshlrev_b32_e32 v52, 16, v138
	v_and_b32_e32 v53, 0xffff0000, v138
	v_lshlrev_b32_e32 v54, 16, v139
	v_and_b32_e32 v55, 0xffff0000, v139
	v_pk_mul_f32 v[48:49], v[58:59], v[48:49] op_sel_hi:[0,1]
	v_pk_mul_f32 v[50:51], v[58:59], v[50:51] op_sel_hi:[0,1]
	v_pk_mul_f32 v[52:53], v[58:59], v[52:53] op_sel_hi:[0,1]
	v_pk_mul_f32 v[54:55], v[58:59], v[54:55] op_sel_hi:[0,1]
	v_pk_mul_f32 v[48:49], v[32:33], v[48:49]
	v_pk_mul_f32 v[50:51], v[34:35], v[50:51]
	v_pk_mul_f32 v[52:53], v[36:37], v[52:53]
	v_pk_mul_f32 v[54:55], v[38:39], v[54:55]
	global_store_dwordx4 v56, v[48:51], s[16:17] offset:512
	global_store_dwordx4 v56, v[52:55], s[16:17] offset:528
	s_nop 1
	v_lshlrev_b32_e32 v56, 1, v13
	v_mov_b32_e32 v58, v21
	s_waitcnt vmcnt(25)
	v_lshlrev_b32_e32 v48, 16, v140
	v_and_b32_e32 v49, 0xffff0000, v140
	v_lshlrev_b32_e32 v50, 16, v141
	v_and_b32_e32 v51, 0xffff0000, v141
	v_lshlrev_b32_e32 v52, 16, v142
	v_and_b32_e32 v53, 0xffff0000, v142
	v_lshlrev_b32_e32 v54, 16, v143
	v_and_b32_e32 v55, 0xffff0000, v143
	v_pk_mul_f32 v[48:49], v[58:59], v[48:49] op_sel_hi:[0,1]
	v_pk_mul_f32 v[50:51], v[58:59], v[50:51] op_sel_hi:[0,1]
	v_pk_mul_f32 v[52:53], v[58:59], v[52:53] op_sel_hi:[0,1]
	v_pk_mul_f32 v[54:55], v[58:59], v[54:55] op_sel_hi:[0,1]
	v_pk_mul_f32 v[48:49], v[24:25], v[48:49]
	v_pk_mul_f32 v[50:51], v[26:27], v[50:51]
	v_pk_mul_f32 v[52:53], v[28:29], v[52:53]
	v_pk_mul_f32 v[54:55], v[30:31], v[54:55]
	global_store_dwordx4 v56, v[48:51], s[16:17]
	global_store_dwordx4 v56, v[52:55], s[16:17] offset:16
	s_nop 1
	s_waitcnt vmcnt(26)
	v_lshlrev_b32_e32 v48, 16, v144
	v_and_b32_e32 v49, 0xffff0000, v144
	v_lshlrev_b32_e32 v50, 16, v145
	v_and_b32_e32 v51, 0xffff0000, v145
	v_lshlrev_b32_e32 v52, 16, v146
	v_and_b32_e32 v53, 0xffff0000, v146
	v_lshlrev_b32_e32 v54, 16, v147
	v_and_b32_e32 v55, 0xffff0000, v147
	v_pk_mul_f32 v[48:49], v[58:59], v[48:49] op_sel_hi:[0,1]
	v_pk_mul_f32 v[50:51], v[58:59], v[50:51] op_sel_hi:[0,1]
	v_pk_mul_f32 v[52:53], v[58:59], v[52:53] op_sel_hi:[0,1]
	v_pk_mul_f32 v[54:55], v[58:59], v[54:55] op_sel_hi:[0,1]
	v_pk_mul_f32 v[48:49], v[32:33], v[48:49]
	v_pk_mul_f32 v[50:51], v[34:35], v[50:51]
	v_pk_mul_f32 v[52:53], v[36:37], v[52:53]
	v_pk_mul_f32 v[54:55], v[38:39], v[54:55]
	global_store_dwordx4 v56, v[48:51], s[16:17] offset:512
	global_store_dwordx4 v56, v[52:55], s[16:17] offset:528
	s_nop 1
	v_lshlrev_b32_e32 v56, 1, v14
	v_mov_b32_e32 v58, v22
	s_waitcnt vmcnt(27)
	v_lshlrev_b32_e32 v48, 16, v148
	v_and_b32_e32 v49, 0xffff0000, v148
	v_lshlrev_b32_e32 v50, 16, v149
	v_and_b32_e32 v51, 0xffff0000, v149
	v_lshlrev_b32_e32 v52, 16, v150
	v_and_b32_e32 v53, 0xffff0000, v150
	v_lshlrev_b32_e32 v54, 16, v151
	v_and_b32_e32 v55, 0xffff0000, v151
	v_pk_mul_f32 v[48:49], v[58:59], v[48:49] op_sel_hi:[0,1]
	v_pk_mul_f32 v[50:51], v[58:59], v[50:51] op_sel_hi:[0,1]
	v_pk_mul_f32 v[52:53], v[58:59], v[52:53] op_sel_hi:[0,1]
	v_pk_mul_f32 v[54:55], v[58:59], v[54:55] op_sel_hi:[0,1]
	v_pk_mul_f32 v[48:49], v[24:25], v[48:49]
	v_pk_mul_f32 v[50:51], v[26:27], v[50:51]
	v_pk_mul_f32 v[52:53], v[28:29], v[52:53]
	v_pk_mul_f32 v[54:55], v[30:31], v[54:55]
	global_store_dwordx4 v56, v[48:51], s[16:17]
	global_store_dwordx4 v56, v[52:55], s[16:17] offset:16
	s_nop 1
	s_waitcnt vmcnt(28)
	v_lshlrev_b32_e32 v48, 16, v152
	v_and_b32_e32 v49, 0xffff0000, v152
	v_lshlrev_b32_e32 v50, 16, v153
	v_and_b32_e32 v51, 0xffff0000, v153
	v_lshlrev_b32_e32 v52, 16, v154
	v_and_b32_e32 v53, 0xffff0000, v154
	v_lshlrev_b32_e32 v54, 16, v155
	v_and_b32_e32 v55, 0xffff0000, v155
	v_pk_mul_f32 v[48:49], v[58:59], v[48:49] op_sel_hi:[0,1]
	v_pk_mul_f32 v[50:51], v[58:59], v[50:51] op_sel_hi:[0,1]
	v_pk_mul_f32 v[52:53], v[58:59], v[52:53] op_sel_hi:[0,1]
	v_pk_mul_f32 v[54:55], v[58:59], v[54:55] op_sel_hi:[0,1]
	v_pk_mul_f32 v[48:49], v[32:33], v[48:49]
	v_pk_mul_f32 v[50:51], v[34:35], v[50:51]
	v_pk_mul_f32 v[52:53], v[36:37], v[52:53]
	v_pk_mul_f32 v[54:55], v[38:39], v[54:55]
	global_store_dwordx4 v56, v[48:51], s[16:17] offset:512
	global_store_dwordx4 v56, v[52:55], s[16:17] offset:528
	s_nop 1
	v_lshlrev_b32_e32 v56, 1, v15
	v_mov_b32_e32 v58, v23
	s_waitcnt vmcnt(29)
	v_lshlrev_b32_e32 v48, 16, v156
	v_and_b32_e32 v49, 0xffff0000, v156
	v_lshlrev_b32_e32 v50, 16, v157
	v_and_b32_e32 v51, 0xffff0000, v157
	v_lshlrev_b32_e32 v52, 16, v158
	v_and_b32_e32 v53, 0xffff0000, v158
	v_lshlrev_b32_e32 v54, 16, v159
	v_and_b32_e32 v55, 0xffff0000, v159
	v_pk_mul_f32 v[48:49], v[58:59], v[48:49] op_sel_hi:[0,1]
	v_pk_mul_f32 v[50:51], v[58:59], v[50:51] op_sel_hi:[0,1]
	v_pk_mul_f32 v[52:53], v[58:59], v[52:53] op_sel_hi:[0,1]
	v_pk_mul_f32 v[54:55], v[58:59], v[54:55] op_sel_hi:[0,1]
	v_pk_mul_f32 v[48:49], v[24:25], v[48:49]
	v_pk_mul_f32 v[50:51], v[26:27], v[50:51]
	v_pk_mul_f32 v[52:53], v[28:29], v[52:53]
	v_pk_mul_f32 v[54:55], v[30:31], v[54:55]
	global_store_dwordx4 v56, v[48:51], s[16:17]
	global_store_dwordx4 v56, v[52:55], s[16:17] offset:16
	s_nop 1
	s_waitcnt vmcnt(30)
	v_lshlrev_b32_e32 v48, 16, v160
	v_and_b32_e32 v49, 0xffff0000, v160
	v_lshlrev_b32_e32 v50, 16, v161
	v_and_b32_e32 v51, 0xffff0000, v161
	v_lshlrev_b32_e32 v52, 16, v162
	v_and_b32_e32 v53, 0xffff0000, v162
	v_lshlrev_b32_e32 v54, 16, v163
	v_and_b32_e32 v55, 0xffff0000, v163
	v_pk_mul_f32 v[48:49], v[58:59], v[48:49] op_sel_hi:[0,1]
	v_pk_mul_f32 v[50:51], v[58:59], v[50:51] op_sel_hi:[0,1]
	v_pk_mul_f32 v[52:53], v[58:59], v[52:53] op_sel_hi:[0,1]
	v_pk_mul_f32 v[54:55], v[58:59], v[54:55] op_sel_hi:[0,1]
	v_pk_mul_f32 v[48:49], v[32:33], v[48:49]
	v_pk_mul_f32 v[50:51], v[34:35], v[50:51]
	v_pk_mul_f32 v[52:53], v[36:37], v[52:53]
	v_pk_mul_f32 v[54:55], v[38:39], v[54:55]
	global_store_dwordx4 v56, v[48:51], s[16:17] offset:512
	global_store_dwordx4 v56, v[52:55], s[16:17] offset:528
	s_nop 1
	s_cbranch_scc1 .LBB0_1812
